# GQA and MLA attention inner loops: per-element v_fmamk (x*scale - m*scale) packed as v_pk_fma_f32 in the 3 groups the compiler left scalar (bit-identical fma)
# speedup vs baseline: 1.0040x; 1.0040x over previous
.LBB0_696:
	v_cndmask_b32_e64 v149, v106, v110, s[8:9]
	v_mul_f32_e32 v150, 0xbe38aa3b, v149
	v_pk_fma_f32 v[50:51], v[50:51], s[94:95], v[150:151] op_sel_hi:[1,0,0]
	v_pk_fma_f32 v[52:53], v[52:53], s[94:95], v[150:151] op_sel_hi:[1,0,0]
	v_pk_fma_f32 v[54:55], v[54:55], s[94:95], v[150:151] op_sel_hi:[1,0,0]
	v_pk_fma_f32 v[56:57], v[56:57], s[94:95], v[150:151] op_sel_hi:[1,0,0]
	v_pk_fma_f32 v[58:59], v[58:59], s[94:95], v[150:151] op_sel_hi:[1,0,0]
	v_pk_fma_f32 v[60:61], v[60:61], s[94:95], v[150:151] op_sel_hi:[1,0,0]
	v_pk_fma_f32 v[62:63], v[62:63], s[94:95], v[150:151] op_sel_hi:[1,0,0]
	v_pk_fma_f32 v[64:65], v[64:65], s[94:95], v[150:151] op_sel_hi:[1,0,0]
	v_exp_f32_e32 v106, v50
	v_exp_f32_e32 v121, v51
	v_exp_f32_e32 v107, v52
	v_exp_f32_e32 v120, v53
	v_exp_f32_e32 v108, v54
	v_exp_f32_e32 v119, v55
	v_exp_f32_e32 v109, v56
	v_exp_f32_e32 v118, v57
	v_exp_f32_e32 v110, v58
	v_exp_f32_e32 v117, v59
	v_exp_f32_e32 v111, v60
	v_exp_f32_e32 v116, v61
	v_exp_f32_e32 v112, v62
	v_exp_f32_e32 v115, v63
	v_exp_f32_e32 v113, v64
	v_exp_f32_e32 v114, v65
	v_pk_fma_f32 v[236:237], v[34:35], s[94:95], v[150:151] op_sel_hi:[1,0,0]
	v_pk_fma_f32 v[238:239], v[36:37], s[94:95], v[150:151] op_sel_hi:[1,0,0]
	v_pk_fma_f32 v[240:241], v[38:39], s[94:95], v[150:151] op_sel_hi:[1,0,0]
	v_pk_fma_f32 v[242:243], v[40:41], s[94:95], v[150:151] op_sel_hi:[1,0,0]
	v_pk_fma_f32 v[244:245], v[42:43], s[94:95], v[150:151] op_sel_hi:[1,0,0]
	v_pk_fma_f32 v[246:247], v[44:45], s[94:95], v[150:151] op_sel_hi:[1,0,0]
	v_pk_fma_f32 v[248:249], v[46:47], s[94:95], v[150:151] op_sel_hi:[1,0,0]
	v_pk_fma_f32 v[250:251], v[48:49], s[94:95], v[150:151] op_sel_hi:[1,0,0]
	s_waitcnt lgkmcnt(0)
	s_barrier
	ds_read_b128 v[34:37], v138 offset:16384
	ds_read_b128 v[38:41], v138 offset:24576
	ds_read_b128 v[166:169], v142 offset:16384
	ds_read_b128 v[170:173], v142 offset:24576
	v_exp_f32_e32 v159, v236
	v_exp_f32_e32 v160, v237
	s_waitcnt lgkmcnt(3)
	v_mfma_f32_32x32x16_bf16 v[50:65], v[34:37], v[78:81], 0
	v_exp_f32_e32 v161, v238
	v_exp_f32_e32 v162, v239
	v_exp_f32_e32 v163, v240
	v_exp_f32_e32 v153, v242
	v_exp_f32_e32 v154, v243
	v_exp_f32_e32 v155, v244
	v_exp_f32_e32 v156, v245
	s_waitcnt lgkmcnt(2)
	v_mfma_f32_32x32x16_bf16 v[34:49], v[38:41], v[78:81], 0
	v_exp_f32_e32 v157, v246
	v_exp_f32_e32 v158, v247
	v_exp_f32_e32 v164, v249
	v_exp_f32_e32 v165, v250
	v_exp_f32_e32 v150, v251
	s_waitcnt lgkmcnt(1)
	v_mfma_f32_32x32x16_bf16 v[50:65], v[166:169], v[70:73], v[50:65]
	s_waitcnt lgkmcnt(0)
	v_mfma_f32_32x32x16_bf16 v[34:49], v[170:173], v[70:73], v[34:49]
	ds_read_b128 v[166:169], v144 offset:16384
	ds_read_b128 v[170:173], v144 offset:24576
	s_waitcnt lgkmcnt(1)
	v_mfma_f32_32x32x16_bf16 v[50:65], v[166:169], v[66:69], v[50:65]
	s_waitcnt lgkmcnt(0)
	v_mfma_f32_32x32x16_bf16 v[34:49], v[170:173], v[66:69], v[34:49]
	ds_read_b128 v[166:169], v143 offset:16384
	ds_read_b128 v[170:173], v143 offset:24576
	s_waitcnt lgkmcnt(1)
	v_mfma_f32_32x32x16_bf16 v[50:65], v[166:169], v[74:77], v[50:65]
	v_exp_f32_e32 v167, v248
	v_add_f32_e32 v151, 0, v106
	v_add_f32_e32 v151, v121, v151
	v_add_f32_e32 v151, v107, v151
	v_add_f32_e32 v151, v120, v151
	v_add_f32_e32 v151, v108, v151
	v_add_f32_e32 v151, v119, v151
	v_add_f32_e32 v151, v109, v151
	v_add_f32_e32 v151, v118, v151
	v_add_f32_e32 v151, v110, v151
	v_add_f32_e32 v151, v117, v151
	v_add_f32_e32 v151, v111, v151
	v_add_f32_e32 v151, v116, v151
	v_add_f32_e32 v151, v112, v151
	v_add_f32_e32 v151, v115, v151
	v_add_f32_e32 v151, v113, v151
	v_add_f32_e32 v151, v114, v151
	v_add_f32_e32 v151, v159, v151
	v_exp_f32_e32 v166, v241
	v_add_f32_e32 v151, v160, v151
	v_add_f32_e32 v151, v161, v151
	v_add_f32_e32 v151, v162, v151
	v_add_f32_e32 v151, v163, v151
	v_add_f32_e32 v151, v166, v151
	v_add_f32_e32 v151, v153, v151
	v_add_f32_e32 v151, v154, v151
	v_add_f32_e32 v151, v155, v151
	v_add_f32_e32 v151, v156, v151
	s_waitcnt lgkmcnt(0)
	v_mfma_f32_32x32x16_bf16 v[34:49], v[170:173], v[74:77], v[34:49]
	v_add_f32_e32 v151, v157, v151
	v_add_f32_e32 v151, v158, v151
	v_add_f32_e32 v151, v167, v151
	v_add_f32_e32 v151, v164, v151
	v_add_f32_e32 v151, v165, v151
	v_add_f32_e32 v151, v150, v151
	v_mov_b32_e32 v152, v151
	v_cvt_pk_bf16_f32 v106, v106, v121
	v_cvt_pk_bf16_f32 v107, v107, v120
	v_cvt_pk_bf16_f32 v108, v108, v119
	v_cvt_pk_bf16_f32 v109, v109, v118
	v_cvt_pk_bf16_f32 v110, v110, v117
	v_cvt_pk_bf16_f32 v111, v111, v116
	v_cvt_pk_bf16_f32 v112, v112, v115
	v_cvt_pk_bf16_f32 v113, v113, v114
	v_cvt_pk_bf16_f32 v114, v159, v160
	v_cvt_pk_bf16_f32 v115, v161, v162
	v_cvt_pk_bf16_f32 v116, v163, v166
	v_cvt_pk_bf16_f32 v117, v153, v154
	v_cvt_pk_bf16_f32 v118, v155, v156
	v_cvt_pk_bf16_f32 v119, v157, v158
	v_cvt_pk_bf16_f32 v120, v167, v164
	v_cvt_pk_bf16_f32 v121, v165, v150
	s_nop 1
	v_permlane32_swap_b32_e32 v151, v152
	v_permlane32_swap_b32_e32 v106, v108
	v_permlane32_swap_b32_e32 v107, v109
	v_permlane32_swap_b32_e32 v110, v112
	v_permlane32_swap_b32_e32 v111, v113
	v_permlane32_swap_b32_e32 v114, v116
	v_permlane32_swap_b32_e32 v115, v117
	v_permlane32_swap_b32_e32 v118, v120
	v_permlane32_swap_b32_e32 v119, v121
	s_cmp_ge_u32 s19, s18
	s_cselect_b64 s[10:11], -1, 0
	s_and_b64 vcc, exec, s[10:11]
	s_cbranch_vccnz .LBB0_698
	v_add_co_u32_e32 v82, vcc, 0x1ed86000, v128
	s_nop 1
	v_addc_co_u32_e32 v83, vcc, 0, v129, vcc
	v_add_co_u32_e32 v86, vcc, 0x1ed86000, v126
	global_load_dwordx4 v[82:85], v[82:83], off offset:1088
	s_nop 0
	v_addc_co_u32_e32 v87, vcc, 0, v127, vcc
	v_add_co_u32_e32 v88, vcc, 0x1eda4000, v126
	s_nop 1
	v_addc_co_u32_e32 v89, vcc, 0, v127, vcc
	global_load_dwordx4 v[90:93], v[86:87], off offset:832
	s_nop 0
	global_load_dwordx4 v[86:89], v[88:89], off offset:2880

.LBB0_702:
	v_cndmask_b32_e64 v110, v106, v149, s[8:9]
	v_mul_f32_e32 v94, 0xbe38aa3b, v110
	v_pk_fma_f32 v[50:51], v[50:51], s[94:95], v[94:95] op_sel_hi:[1,0,0]
	v_pk_fma_f32 v[52:53], v[52:53], s[94:95], v[94:95] op_sel_hi:[1,0,0]
	v_pk_fma_f32 v[54:55], v[54:55], s[94:95], v[94:95] op_sel_hi:[1,0,0]
	v_pk_fma_f32 v[56:57], v[56:57], s[94:95], v[94:95] op_sel_hi:[1,0,0]
	v_pk_fma_f32 v[58:59], v[58:59], s[94:95], v[94:95] op_sel_hi:[1,0,0]
	v_pk_fma_f32 v[60:61], v[60:61], s[94:95], v[94:95] op_sel_hi:[1,0,0]
	v_pk_fma_f32 v[62:63], v[62:63], s[94:95], v[94:95] op_sel_hi:[1,0,0]
	v_pk_fma_f32 v[64:65], v[64:65], s[94:95], v[94:95] op_sel_hi:[1,0,0]
	v_exp_f32_e32 v120, v50
	v_exp_f32_e32 v128, v51
	v_exp_f32_e32 v121, v52
	v_exp_f32_e32 v129, v53
	v_exp_f32_e32 v126, v54
	v_exp_f32_e32 v149, v55
	v_exp_f32_e32 v127, v56
	v_exp_f32_e32 v150, v57
	v_exp_f32_e32 v112, v58
	v_exp_f32_e32 v115, v59
	v_exp_f32_e32 v113, v60
	v_exp_f32_e32 v116, v61
	v_exp_f32_e32 v114, v62
	v_exp_f32_e32 v117, v63
	v_exp_f32_e32 v118, v64
	v_exp_f32_e32 v119, v65
	v_pk_fma_f32 v[108:109], v[34:35], s[94:95], v[94:95] op_sel_hi:[1,0,0]
	v_add_f32_e32 v34, v146, v147
	v_fmac_f32_e32 v34, v145, v136
	v_add_f32_e32 v136, v151, v152
	v_pk_fma_f32 v[106:107], v[36:37], s[94:95], v[94:95] op_sel_hi:[1,0,0]
	v_pk_fma_f32 v[102:103], v[38:39], s[94:95], v[94:95] op_sel_hi:[1,0,0]
	v_pk_fma_f32 v[98:99], v[40:41], s[94:95], v[94:95] op_sel_hi:[1,0,0]
	v_pk_fma_f32 v[96:97], v[42:43], s[94:95], v[94:95] op_sel_hi:[1,0,0]
	v_pk_fma_f32 v[104:105], v[44:45], s[94:95], v[94:95] op_sel_hi:[1,0,0]
	v_pk_fma_f32 v[100:101], v[46:47], s[94:95], v[94:95] op_sel_hi:[1,0,0]
	v_pk_fma_f32 v[94:95], v[48:49], s[94:95], v[94:95] op_sel_hi:[1,0,0]
	v_fmac_f32_e32 v136, v34, v148
	v_lshl_add_u64 v[122:123], v[122:123], 0, s[24:25]
	v_lshl_add_u64 v[124:125], v[124:125], 0, s[24:25]
	s_add_i32 s19, s19, 2
	s_and_b64 vcc, exec, s[10:11]
	s_waitcnt lgkmcnt(0)
	s_barrier
	s_cbranch_vccnz .LBB0_783
	v_mov_b32_e32 v145, v111
	s_branch .LBB0_692

.LBB0_923:
	v_cndmask_b32_e64 v159, v114, v118, s[8:9]
	v_mul_f32_e32 v160, 0xbe16c740, v159
	v_pk_fma_f32 v[50:51], v[50:51], s[96:97], v[160:161] op_sel_hi:[1,0,0]
	v_pk_fma_f32 v[52:53], v[52:53], s[96:97], v[160:161] op_sel_hi:[1,0,0]
	v_pk_fma_f32 v[54:55], v[54:55], s[96:97], v[160:161] op_sel_hi:[1,0,0]
	v_pk_fma_f32 v[56:57], v[56:57], s[96:97], v[160:161] op_sel_hi:[1,0,0]
	v_pk_fma_f32 v[58:59], v[58:59], s[96:97], v[160:161] op_sel_hi:[1,0,0]
	v_pk_fma_f32 v[60:61], v[60:61], s[96:97], v[160:161] op_sel_hi:[1,0,0]
	v_pk_fma_f32 v[62:63], v[62:63], s[96:97], v[160:161] op_sel_hi:[1,0,0]
	v_pk_fma_f32 v[64:65], v[64:65], s[96:97], v[160:161] op_sel_hi:[1,0,0]
	v_exp_f32_e32 v114, v50
	v_exp_f32_e32 v129, v51
	v_exp_f32_e32 v115, v52
	v_exp_f32_e32 v128, v53
	v_exp_f32_e32 v116, v54
	v_exp_f32_e32 v127, v55
	v_exp_f32_e32 v117, v56
	v_exp_f32_e32 v126, v57
	v_exp_f32_e32 v118, v58
	v_exp_f32_e32 v125, v59
	v_exp_f32_e32 v119, v60
	v_exp_f32_e32 v124, v61
	v_exp_f32_e32 v120, v62
	v_exp_f32_e32 v123, v63
	v_exp_f32_e32 v121, v64
	v_exp_f32_e32 v122, v65
	v_pk_fma_f32 v[236:237], v[34:35], s[96:97], v[160:161] op_sel_hi:[1,0,0]
	v_pk_fma_f32 v[238:239], v[36:37], s[96:97], v[160:161] op_sel_hi:[1,0,0]
	v_pk_fma_f32 v[240:241], v[38:39], s[96:97], v[160:161] op_sel_hi:[1,0,0]
	v_pk_fma_f32 v[242:243], v[40:41], s[96:97], v[160:161] op_sel_hi:[1,0,0]
	v_pk_fma_f32 v[244:245], v[42:43], s[96:97], v[160:161] op_sel_hi:[1,0,0]
	v_pk_fma_f32 v[246:247], v[44:45], s[96:97], v[160:161] op_sel_hi:[1,0,0]
	v_pk_fma_f32 v[248:249], v[46:47], s[96:97], v[160:161] op_sel_hi:[1,0,0]
	v_pk_fma_f32 v[250:251], v[48:49], s[96:97], v[160:161] op_sel_hi:[1,0,0]
	s_waitcnt lgkmcnt(0)
	s_barrier
	ds_read_b128 v[34:37], v149 offset:16384
	ds_read_b128 v[38:41], v149 offset:24576
	ds_read_b128 v[176:179], v152 offset:16384
	ds_read_b128 v[180:183], v152 offset:24576
	v_exp_f32_e32 v168, v236
	v_exp_f32_e32 v169, v237
	s_waitcnt lgkmcnt(3)
	v_mfma_f32_32x32x16_bf16 v[50:65], v[34:37], v[78:81], 0
	v_exp_f32_e32 v170, v238
	v_exp_f32_e32 v171, v239
	v_exp_f32_e32 v172, v240
	v_exp_f32_e32 v173, v241
	v_exp_f32_e32 v163, v244
	v_exp_f32_e32 v164, v245
	v_exp_f32_e32 v165, v246
	s_waitcnt lgkmcnt(2)
	v_mfma_f32_32x32x16_bf16 v[34:49], v[38:41], v[78:81], 0
	v_exp_f32_e32 v166, v247
	v_exp_f32_e32 v167, v248
	v_exp_f32_e32 v174, v249
	v_exp_f32_e32 v175, v250
	v_exp_f32_e32 v160, v251
	s_waitcnt lgkmcnt(1)
	v_mfma_f32_32x32x16_bf16 v[50:65], v[176:179], v[74:77], v[50:65]
	s_waitcnt lgkmcnt(0)
	v_mfma_f32_32x32x16_bf16 v[34:49], v[180:183], v[74:77], v[34:49]
	ds_read_b128 v[176:179], v151 offset:16384
	ds_read_b128 v[180:183], v151 offset:24576
	s_waitcnt lgkmcnt(1)
	v_mfma_f32_32x32x16_bf16 v[50:65], v[176:179], v[70:73], v[50:65]
	s_waitcnt lgkmcnt(0)
	v_mfma_f32_32x32x16_bf16 v[34:49], v[180:183], v[70:73], v[34:49]
	ds_read_b128 v[176:179], v150 offset:16384
	ds_read_b128 v[180:183], v150 offset:24576
	s_waitcnt lgkmcnt(1)
	v_mfma_f32_32x32x16_bf16 v[50:65], v[176:179], v[66:69], v[50:65]
	s_waitcnt lgkmcnt(0)
	v_mfma_f32_32x32x16_bf16 v[34:49], v[180:183], v[66:69], v[34:49]
	ds_read_b128 v[176:179], v153 offset:16384
	ds_read_b128 v[180:183], v153 offset:24576
	s_waitcnt lgkmcnt(1)
	v_mfma_f32_32x32x16_bf16 v[50:65], v[176:179], v[86:89], v[50:65]
	s_waitcnt lgkmcnt(0)
	v_mfma_f32_32x32x16_bf16 v[34:49], v[180:183], v[86:89], v[34:49]
	ds_read_b128 v[176:179], v154 offset:16384
	ds_read_b128 v[180:183], v154 offset:24576
	s_waitcnt lgkmcnt(1)
	v_mfma_f32_32x32x16_bf16 v[50:65], v[176:179], v[82:85], v[50:65]
	v_exp_f32_e32 v176, v242
	v_add_f32_e32 v161, 0, v114
	v_add_f32_e32 v161, v129, v161
	v_add_f32_e32 v161, v115, v161
	v_add_f32_e32 v161, v128, v161
	v_add_f32_e32 v161, v116, v161
	v_add_f32_e32 v161, v127, v161
	v_add_f32_e32 v161, v117, v161
	v_add_f32_e32 v161, v126, v161
	v_add_f32_e32 v161, v118, v161
	v_add_f32_e32 v161, v125, v161
	v_add_f32_e32 v161, v119, v161
	v_add_f32_e32 v161, v124, v161
	v_add_f32_e32 v161, v120, v161
	v_add_f32_e32 v161, v123, v161
	v_add_f32_e32 v161, v121, v161
	v_add_f32_e32 v161, v122, v161
	v_add_f32_e32 v161, v168, v161
	v_add_f32_e32 v161, v169, v161
	v_add_f32_e32 v161, v170, v161
	v_exp_f32_e32 v177, v243
	v_add_f32_e32 v161, v171, v161
	v_add_f32_e32 v161, v172, v161
	v_add_f32_e32 v161, v173, v161
	v_add_f32_e32 v161, v176, v161
	v_add_f32_e32 v161, v177, v161
	v_add_f32_e32 v161, v163, v161
	v_add_f32_e32 v161, v164, v161
	s_waitcnt lgkmcnt(0)
	v_mfma_f32_32x32x16_bf16 v[34:49], v[180:183], v[82:85], v[34:49]
	v_add_f32_e32 v161, v165, v161
	v_add_f32_e32 v161, v166, v161
	v_add_f32_e32 v161, v167, v161
	v_add_f32_e32 v161, v174, v161
	v_add_f32_e32 v161, v175, v161
	v_add_f32_e32 v161, v160, v161
	v_mov_b32_e32 v162, v161
	v_cvt_pk_bf16_f32 v114, v114, v129
	v_cvt_pk_bf16_f32 v115, v115, v128
	v_cvt_pk_bf16_f32 v116, v116, v127
	v_cvt_pk_bf16_f32 v117, v117, v126
	v_cvt_pk_bf16_f32 v118, v118, v125
	v_cvt_pk_bf16_f32 v119, v119, v124
	v_cvt_pk_bf16_f32 v120, v120, v123
	v_cvt_pk_bf16_f32 v121, v121, v122
	v_cvt_pk_bf16_f32 v122, v168, v169
	v_cvt_pk_bf16_f32 v123, v170, v171
	v_cvt_pk_bf16_f32 v124, v172, v173
	v_cvt_pk_bf16_f32 v125, v176, v177
	v_cvt_pk_bf16_f32 v126, v163, v164
	v_cvt_pk_bf16_f32 v127, v165, v166
	v_cvt_pk_bf16_f32 v128, v167, v174
	v_cvt_pk_bf16_f32 v129, v175, v160
	s_nop 1
	v_permlane32_swap_b32_e32 v161, v162
	v_permlane32_swap_b32_e32 v114, v116
	v_permlane32_swap_b32_e32 v115, v117
	v_permlane32_swap_b32_e32 v118, v120
	v_permlane32_swap_b32_e32 v119, v121
	v_permlane32_swap_b32_e32 v122, v124
	v_permlane32_swap_b32_e32 v123, v125
	v_permlane32_swap_b32_e32 v126, v128
	v_permlane32_swap_b32_e32 v127, v129
	s_cmp_gt_u32 s24, 32
	s_cselect_b64 s[16:17], -1, 0
	s_and_b64 vcc, exec, s[16:17]
	s_cbranch_vccnz .LBB0_925
	v_add_co_u32_e32 v90, vcc, 0x15d11000, v138
	s_nop 1
	v_addc_co_u32_e32 v91, vcc, 0, v139, vcc
	v_add_co_u32_e32 v94, vcc, 0x15d11000, v136
	global_load_dwordx4 v[90:93], v[90:91], off offset:3072
	s_nop 0
	v_addc_co_u32_e32 v95, vcc, 0, v137, vcc
	v_add_co_u32_e32 v96, vcc, 0x15d21000, v136
	s_nop 1
	v_addc_co_u32_e32 v97, vcc, 0, v137, vcc
	global_load_dwordx4 v[98:101], v[94:95], off offset:2304
	s_nop 0
	global_load_dwordx4 v[94:97], v[96:97], off offset:2304

.LBB0_929:
	v_cndmask_b32_e64 v118, v114, v159, s[8:9]
	v_mul_f32_e32 v102, 0xbe16c740, v118
	v_pk_fma_f32 v[50:51], v[50:51], s[96:97], v[102:103] op_sel_hi:[1,0,0]
	v_pk_fma_f32 v[52:53], v[52:53], s[96:97], v[102:103] op_sel_hi:[1,0,0]
	v_pk_fma_f32 v[54:55], v[54:55], s[96:97], v[102:103] op_sel_hi:[1,0,0]
	v_pk_fma_f32 v[56:57], v[56:57], s[96:97], v[102:103] op_sel_hi:[1,0,0]
	v_pk_fma_f32 v[58:59], v[58:59], s[96:97], v[102:103] op_sel_hi:[1,0,0]
	v_pk_fma_f32 v[60:61], v[60:61], s[96:97], v[102:103] op_sel_hi:[1,0,0]
	v_pk_fma_f32 v[62:63], v[62:63], s[96:97], v[102:103] op_sel_hi:[1,0,0]
	v_pk_fma_f32 v[64:65], v[64:65], s[96:97], v[102:103] op_sel_hi:[1,0,0]
	v_exp_f32_e32 v128, v50
	v_exp_f32_e32 v138, v51
	v_exp_f32_e32 v129, v52
	v_exp_f32_e32 v139, v53
	v_exp_f32_e32 v136, v54
	v_exp_f32_e32 v159, v55
	v_exp_f32_e32 v137, v56
	v_exp_f32_e32 v160, v57
	v_exp_f32_e32 v120, v58
	v_exp_f32_e32 v123, v59
	v_exp_f32_e32 v121, v60
	v_exp_f32_e32 v124, v61
	v_exp_f32_e32 v122, v62
	v_exp_f32_e32 v125, v63
	v_exp_f32_e32 v126, v64
	v_exp_f32_e32 v127, v65
	v_pk_fma_f32 v[116:117], v[34:35], s[96:97], v[102:103] op_sel_hi:[1,0,0]
	v_add_f32_e32 v34, v156, v157
	v_fmac_f32_e32 v34, v155, v144
	v_add_f32_e32 v144, v161, v162
	v_pk_fma_f32 v[114:115], v[36:37], s[96:97], v[102:103] op_sel_hi:[1,0,0]
	v_pk_fma_f32 v[110:111], v[38:39], s[96:97], v[102:103] op_sel_hi:[1,0,0]
	v_pk_fma_f32 v[106:107], v[40:41], s[96:97], v[102:103] op_sel_hi:[1,0,0]
	v_pk_fma_f32 v[104:105], v[42:43], s[96:97], v[102:103] op_sel_hi:[1,0,0]
	v_pk_fma_f32 v[112:113], v[44:45], s[96:97], v[102:103] op_sel_hi:[1,0,0]
	v_pk_fma_f32 v[108:109], v[46:47], s[96:97], v[102:103] op_sel_hi:[1,0,0]
	v_pk_fma_f32 v[102:103], v[48:49], s[96:97], v[102:103] op_sel_hi:[1,0,0]
	v_fmac_f32_e32 v144, v34, v158
	s_add_i32 s24, s24, 2
	v_lshl_add_u64 v[132:133], v[132:133], 0, s[2:3]
	v_lshl_add_u64 v[134:135], v[134:135], 0, s[2:3]
	s_and_b64 vcc, exec, s[16:17]
	s_waitcnt lgkmcnt(0)
	s_barrier
	s_cbranch_vccnz .LBB0_932
	v_mov_b32_e32 v155, v119
	s_branch .LBB0_919
